# static s_setprio 1 for waves 4-7 during the attention phase (on top of v27)
# speedup vs baseline: 1.0022x; 1.0022x over previous
; #define LAS __attribute__((address_space(3)))
; #define KARG(i) ({ unsigned long long p_; asm volatile("s_load_dwordx2 %0, %1, %2\n\ts_waitcnt lgkmcnt(0)" : "=s"(p_) : "s"((unsigned long long)__builtin_amdgcn_kernarg_segment_ptr()), "n"((i) * 8)); p_; })
; __global__ void __launch_bounds__(NWAVES * 64, 2) mk_fwd(Args args) {
;     ...
;         for (int repa = 0; repa < REPA; ++repa)
;         for (int v0 = vcu; v0 < 256; v0 += NV) {
;             const int bh = v0 >> 1, b = bh >> 3, h = bh & 7, sel = v0 & 1;
;             {
;                 LAS v4u* kxt = (LAS v4u*)(lds + attn_body::LDS_KX); const v4u* src = (const v4u*)((const unsigned char*)KARG(20) + WS_KXG) + (size_t)bh * SEQ;
; #pragma unroll
;                 for (int j = 0; j < 4; ++j) kxt[tid + 512 * j] = src[tid + 512 * j];
;                 if (tid == 0) { unsigned zz = 0u; asm volatile("" : "+v"(zz)); kxt[SEQ] = (v4u){zz, zz, zz, zz}; }
;                 __syncthreads();
;             }
;             const attn_body::bf16* Zb = (const attn_body::bf16*)Z;
;     ...
;             attn_body::bf16x8 qn0 = {}, qn1 = {}, qn2 = {}, qn3 = {};
; #pragma unroll 1
;             for (int i = 0; i < 4; ++i) {
;     ...
;                 const int qb = QB_OF(i), qbn = (i < 3) ? QB_OF(i + 1) : -1;
;                 attn_body::attn_unit<96>(b, h, qb, Zb + 1024, Zb + 1536, Zb + 2048, (attn_body::bf16*)CAT + 512, (char*)lds_raw, i == 0, qbn, qn0, qn1, qn2, qn3);
;     ...
;             }
.LBB0_235:
	s_lshr_b32 s98, s72, 6
	s_cmp_ge_u32 s98, 4
	s_cbranch_scc0 .Lattn_prio_done
	s_setprio 1

; #define LAS __attribute__((address_space(3)))
; __global__ void __launch_bounds__(NWAVES * 64, 2) mk_fwd(Args args) {
;     ...
;         {
;             const int cp = tid & 255, th = tid >> 8;
;             f32x2 w[31];
; #pragma unroll
;             for (int j = 0; j < 31; ++j) w[j] = *(const f32x2*)(conv_w + j * 512 + 2 * cp);
;             const f32x2 cb = *(const f32x2*)(conv_b + 2 * cp);
;             LAS float* yt = (LAS float*)lds;
;             f32x4 lg0 = *(const f32x4*)(ln_g + 4 * lane), lg1 = *(const f32x4*)(ln_g + 256 + 4 * lane), lb0 = *(const f32x4*)(ln_b + 4 * lane), lb1 = *(const f32x4*)(ln_b + 256 + 4 * lane);
;     ...
;             for (int repc = 0; repc < REPC; ++repc)
;             for (int kt = 0, tile = (G == 256) ? 64 * (vcu >> 5) + (vcu & 31) : vcu; tile < T / 64; ++kt, tile = (G == 256) ? ((kt < 2) ? 64 * (vcu >> 5) + 32 * kt + (vcu & 31) : T) : tile + G) {
.LBB0_352:
	s_setprio 0
	s_lshl_b32 s4, s73, 1
	s_andn2_b32 s4, s4, 63
	s_and_b32 s5, s73, 31
	s_or_b32 s4, s4, s5
	s_and_b64 s[6:7], s[50:51], exec
	s_cselect_b32 s6, s4, s73
	s_cmpk_lt_i32 s6, 0x200
	s_cbranch_scc0 .LBB0_361
	v_lshlrev_b32_e32 v0, 1, v200
	v_and_b32_e32 v20, 0x1fe, v0
	v_mov_b32_e32 v80, 0
	v_lshlrev_b32_e32 v0, 2, v20
	v_mov_b32_e32 v1, v80
	v_lshl_add_u64 v[2:3], s[18:19], 0, v[0:1]
	v_add_co_u32_e32 v4, vcc, 0x1000, v2
	v_lshl_add_u64 v[0:1], s[16:17], 0, v[0:1]
	s_nop 0
	v_addc_co_u32_e32 v5, vcc, 0, v3, vcc
	flat_load_dwordx2 v[82:83], v[2:3]
	flat_load_dwordx2 v[84:85], v[2:3] offset:2048
	flat_load_dwordx2 v[86:87], v[4:5]
	flat_load_dwordx2 v[88:89], v[4:5] offset:2048
	v_add_co_u32_e32 v4, vcc, 0x2000, v2
	v_mov_b32_e32 v17, v80
	s_nop 0
	v_addc_co_u32_e32 v5, vcc, 0, v3, vcc
	v_add_co_u32_e32 v6, vcc, 0x3000, v2
	s_ashr_i32 s5, s72, 6
	s_nop 0
	v_addc_co_u32_e32 v7, vcc, 0, v3, vcc
	flat_load_dwordx2 v[90:91], v[4:5]
	flat_load_dwordx2 v[92:93], v[4:5] offset:2048
	flat_load_dwordx2 v[94:95], v[6:7]
	flat_load_dwordx2 v[96:97], v[6:7] offset:2048
	v_add_co_u32_e32 v4, vcc, 0x4000, v2
	s_movk_i32 s7, 0x1000
	s_nop 0
	v_addc_co_u32_e32 v5, vcc, 0, v3, vcc
	v_add_co_u32_e32 v6, vcc, 0x5000, v2
	s_movk_i32 s8, 0x2000
	s_nop 0
	v_addc_co_u32_e32 v7, vcc, 0, v3, vcc
	flat_load_dwordx2 v[98:99], v[4:5]
	s_waitcnt vmcnt(0)
	flat_load_dwordx2 v[100:101], v[4:5] offset:2048
	flat_load_dwordx2 v[102:103], v[6:7]
	flat_load_dwordx2 v[104:105], v[6:7] offset:2048
	v_add_co_u32_e32 v4, vcc, 0x6000, v2
	s_movk_i32 s9, 0x3000
	s_nop 0
	v_addc_co_u32_e32 v5, vcc, 0, v3, vcc
	v_add_co_u32_e32 v6, vcc, 0x7000, v2
	v_mov_b32_e32 v176, 0x358637bd
	s_nop 0
	v_addc_co_u32_e32 v7, vcc, 0, v3, vcc
	flat_load_dwordx2 v[106:107], v[4:5]
	flat_load_dwordx2 v[108:109], v[4:5] offset:2048
	flat_load_dwordx2 v[110:111], v[6:7]
	flat_load_dwordx2 v[112:113], v[6:7] offset:2048
	v_add_co_u32_e32 v4, vcc, 0x8000, v2
	v_mov_b32_e32 v177, 0x260
	s_nop 0
	v_addc_co_u32_e32 v5, vcc, 0, v3, vcc
	v_add_co_u32_e32 v6, vcc, 0x9000, v2
	s_nop 1
	v_addc_co_u32_e32 v7, vcc, 0, v3, vcc
	flat_load_dwordx2 v[114:115], v[4:5]
	flat_load_dwordx2 v[116:117], v[4:5] offset:2048
	flat_load_dwordx2 v[118:119], v[6:7]
	flat_load_dwordx2 v[120:121], v[6:7] offset:2048
	v_add_co_u32_e32 v4, vcc, 0xa000, v2
	s_nop 1
	v_addc_co_u32_e32 v5, vcc, 0, v3, vcc
	v_add_co_u32_e32 v6, vcc, 0xb000, v2
	s_nop 1
	v_addc_co_u32_e32 v7, vcc, 0, v3, vcc
	flat_load_dwordx2 v[122:123], v[4:5]
	flat_load_dwordx2 v[124:125], v[4:5] offset:2048
	flat_load_dwordx2 v[126:127], v[6:7]
	flat_load_dwordx2 v[128:129], v[6:7] offset:2048
	v_add_co_u32_e32 v4, vcc, 0xc000, v2
	s_nop 1
	v_addc_co_u32_e32 v5, vcc, 0, v3, vcc
	v_add_co_u32_e32 v6, vcc, 0xd000, v2
	s_nop 1
	v_addc_co_u32_e32 v7, vcc, 0, v3, vcc
	flat_load_dwordx2 v[130:131], v[4:5]
	flat_load_dwordx2 v[132:133], v[4:5] offset:2048
	flat_load_dwordx2 v[134:135], v[6:7]
	flat_load_dwordx2 v[136:137], v[6:7] offset:2048
	v_add_co_u32_e32 v4, vcc, 0xe000, v2
	s_nop 1
	v_addc_co_u32_e32 v5, vcc, 0, v3, vcc
	v_add_co_u32_e32 v2, vcc, 0xf000, v2
	s_nop 1
	v_addc_co_u32_e32 v3, vcc, 0, v3, vcc
	flat_load_dwordx2 v[138:139], v[4:5]
	flat_load_dwordx2 v[140:141], v[4:5] offset:2048
	flat_load_dwordx2 v[142:143], v[2:3]
	flat_load_dwordx2 v[144:145], v[0:1]
	v_lshlrev_b32_e32 v0, 2, v200
	v_and_b32_e32 v21, 0xfc, v0
	v_lshlrev_b32_e32 v16, 2, v21
	v_lshl_add_u64 v[8:9], s[12:13], 0, v[16:17]
	v_lshl_add_u64 v[18:19], s[14:15], 0, v[16:17]
	flat_load_dwordx4 v[0:3], v[8:9]
	flat_load_dwordx4 v[4:7], v[8:9] offset:1024
	s_nop 0
	flat_load_dwordx4 v[8:11], v[18:19]
	flat_load_dwordx4 v[12:15], v[18:19] offset:1024
	v_lshlrev_b32_e32 v18, 1, v20
	v_mov_b32_e32 v19, v80
	v_lshl_add_u64 v[18:19], s[2:3], 0, v[18:19]
	s_mov_b64 s[14:15], 0x8000000
	v_mbcnt_lo_u32_b32 v17, -1, 0
	v_lshl_add_u64 v[146:147], v[18:19], 0, s[14:15]
	s_or_b32 s15, s4, 32
	s_lshl_b32 s4, s5, 14
	v_mbcnt_hi_u32_b32 v17, -1, v17
	s_add_i32 s4, s4, 0
	v_and_b32_e32 v19, 64, v17
	v_add_u32_e32 v19, 64, v19
	v_add_u32_e32 v168, s4, v16
	v_xor_b32_e32 v16, 1, v17
	v_cmp_lt_i32_e32 vcc, v16, v19
	s_lshl_b32 s14, s5, 3
	s_mov_b64 s[4:5], 0x14000000
	v_cndmask_b32_e32 v16, v17, v16, vcc
	v_lshlrev_b32_e32 v169, 2, v16
	v_xor_b32_e32 v16, 2, v17
	v_cmp_lt_i32_e32 vcc, v16, v19
	v_ashrrev_i32_e32 v18, 3, v200
	v_and_b32_e32 v166, 0xffffffe0, v18
	v_cndmask_b32_e32 v16, v17, v16, vcc
	v_lshlrev_b32_e32 v170, 2, v16
	v_xor_b32_e32 v16, 4, v17
	v_cmp_lt_i32_e32 vcc, v16, v19
	s_mov_b32 s13, 0
	s_movk_i32 s12, 0x5000
	v_cndmask_b32_e32 v16, v17, v16, vcc
	v_lshlrev_b32_e32 v171, 2, v16
	v_xor_b32_e32 v16, 8, v17
	v_cmp_lt_i32_e32 vcc, v16, v19
	v_sub_u32_e32 v167, 0, v166
	s_nop 0
	v_cndmask_b32_e32 v16, v17, v16, vcc
	v_lshlrev_b32_e32 v172, 2, v16
	v_xor_b32_e32 v16, 16, v17
	v_cmp_lt_i32_e32 vcc, v16, v19
	s_nop 1
	v_cndmask_b32_e32 v16, v17, v16, vcc
	v_lshlrev_b32_e32 v173, 2, v16
	v_xor_b32_e32 v16, 32, v17
	v_cmp_lt_i32_e32 vcc, v16, v19
	s_nop 1
	v_cndmask_b32_e32 v16, v17, v16, vcc
	v_lshlrev_b32_e32 v174, 2, v16
	v_lshlrev_b32_e32 v16, 1, v21
	v_mov_b32_e32 v17, v80
	v_lshl_add_u64 v[16:17], s[10:11], 0, v[16:17]
	v_lshl_add_u64 v[148:149], v[16:17], 0, s[4:5]
	v_mov_b32_e32 v16, 2
	v_lshlrev_b32_sdwa v16, v16, v200 dst_sel:DWORD dst_unused:UNUSED_PAD src0_sel:DWORD src1_sel:BYTE_0
	v_mov_b32_e32 v17, v80
	v_lshl_add_u64 v[150:151], s[2:3], 0, v[16:17]
	v_mov_b32_e32 v17, 3
	v_lshlrev_b32_e32 v16, 11, v18
	v_lshlrev_b32_sdwa v17, v17, v200 dst_sel:DWORD dst_unused:UNUSED_PAD src0_sel:DWORD src1_sel:BYTE_0
	s_mov_b32 s2, 0xffff0000
	v_and_or_b32 v16, v16, s2, v17
	v_add_u32_e32 v175, 0, v16
	s_movk_i32 s10, 0x1400
	s_mov_b32 s11, 0xf800000
	s_branch .LBB0_355
